# stack + P3 epilogue: second-half gate loads hoisted next to the first half's
# speedup vs baseline: 1.0133x; 1.0133x over previous
.LBB0_408:
	s_add_i32 s4, s62, 0x200
	s_ashr_i32 s5, s4, 31
	s_lshl_b64 s[4:5], s[4:5], 16
	v_lshl_add_u64 v[2:3], v[208:209], 0, s[4:5]
	global_load_dwordx4 v[132:135], v[2:3], off
	global_load_dwordx4 v[136:139], v[2:3], off offset:1024
	v_pk_mul_f32 v[140:141], v[106:107], s[16:17] op_sel_hi:[1,0]
	v_pk_mul_f32 v[142:143], v[104:105], s[16:17] op_sel_hi:[1,0]
	global_load_dwordx4 v[104:107], v[2:3], off offset:2048
	v_pk_mul_f32 v[144:145], v[102:103], s[16:17] op_sel_hi:[1,0]
	v_pk_mul_f32 v[146:147], v[100:101], s[16:17] op_sel_hi:[1,0]
	global_load_dwordx4 v[100:103], v[2:3], off offset:3072
	s_lshl_b32 s4, s59, 9
	s_lshl_b32 s5, s28, 19
	v_pk_mul_f32 v[130:131], v[130:131], s[16:17] op_sel_hi:[1,0]
	v_pk_mul_f32 v[128:129], v[128:129], s[16:17] op_sel_hi:[1,0]
	v_pk_mul_f32 v[126:127], v[126:127], s[16:17] op_sel_hi:[1,0]
	v_pk_mul_f32 v[124:125], v[124:125], s[16:17] op_sel_hi:[1,0]
	v_pk_mul_f32 v[122:123], v[122:123], s[16:17] op_sel_hi:[1,0]
	v_pk_mul_f32 v[120:121], v[120:121], s[16:17] op_sel_hi:[1,0]
	v_pk_mul_f32 v[118:119], v[118:119], s[16:17] op_sel_hi:[1,0]
	v_pk_mul_f32 v[116:117], v[116:117], s[16:17] op_sel_hi:[1,0]
	v_pk_mul_f32 v[114:115], v[114:115], s[16:17] op_sel_hi:[1,0]
	v_pk_mul_f32 v[112:113], v[112:113], s[16:17] op_sel_hi:[1,0]
	v_pk_mul_f32 v[110:111], v[110:111], s[16:17] op_sel_hi:[1,0]
	v_pk_mul_f32 v[108:109], v[108:109], s[16:17] op_sel_hi:[1,0]
	s_add_i32 s5, s5, s4
	v_add_u32_e32 v0, s5, v218
	v_add_u32_e32 v170, 0x8000, v0
	v_pk_mul_f32 v[96:97], v[96:97], s[16:17] op_sel_hi:[1,0]
	v_pk_mul_f32 v[98:99], v[98:99], s[16:17] op_sel_hi:[1,0]
	v_pk_mul_f32 v[88:89], v[88:89], s[16:17] op_sel_hi:[1,0]
	v_pk_mul_f32 v[90:91], v[90:91], s[16:17] op_sel_hi:[1,0]
	v_pk_mul_f32 v[80:81], v[80:81], s[16:17] op_sel_hi:[1,0]
	v_pk_mul_f32 v[82:83], v[82:83], s[16:17] op_sel_hi:[1,0]
	v_pk_mul_f32 v[72:73], v[72:73], s[16:17] op_sel_hi:[1,0]
	v_pk_mul_f32 v[74:75], v[74:75], s[16:17] op_sel_hi:[1,0]
	v_add_co_u32_e32 v2, vcc, s57, v2
	v_pk_mul_f32 v[64:65], v[64:65], s[16:17] op_sel_hi:[1,0]
	s_nop 0
	v_addc_co_u32_e32 v3, vcc, 0, v3, vcc
	global_load_dwordx4 v[224:227], v[2:3], off
	global_load_dwordx4 v[228:231], v[2:3], off offset:1024
	global_load_dwordx4 v[232:235], v[2:3], off offset:2048
	global_load_dwordx4 v[236:239], v[2:3], off offset:3072
	v_pk_mul_f32 v[56:57], v[56:57], s[16:17] op_sel_hi:[1,0]
	v_pk_mul_f32 v[48:49], v[48:49], s[16:17] op_sel_hi:[1,0]
	v_pk_mul_f32 v[40:41], v[40:41], s[16:17] op_sel_hi:[1,0]
	v_pk_mul_f32 v[32:33], v[32:33], s[16:17] op_sel_hi:[1,0]
	v_pk_mul_f32 v[24:25], v[24:25], s[16:17] op_sel_hi:[1,0]
	v_pk_mul_f32 v[16:17], v[16:17], s[16:17] op_sel_hi:[1,0]
	v_pk_mul_f32 v[10:11], v[10:11], s[16:17] op_sel_hi:[1,0]
	v_pk_mul_f32 v[4:5], v[4:5], s[16:17] op_sel_hi:[1,0]
	v_pk_mul_f32 v[6:7], v[6:7], s[16:17] op_sel_hi:[1,0]
	s_and_b64 vcc, exec, s[0:1]
	s_mov_b32 s59, s18
	s_mov_b32 s28, s20
	s_mov_b64 s[36:37], s[26:27]
	s_mov_b64 s[30:31], s[24:25]
	s_mov_b64 s[34:35], s[22:23]
	s_waitcnt vmcnt(4)
	v_cvt_f32_ubyte1_e32 v149, v132
	v_cvt_f32_ubyte0_e32 v148, v132
	v_cvt_f32_ubyte3_e32 v151, v132
	v_cvt_f32_ubyte2_e32 v150, v132
	v_cvt_f32_ubyte1_e32 v153, v133
	v_cvt_f32_ubyte0_e32 v152, v133
	v_cvt_f32_ubyte3_e32 v155, v133
	v_cvt_f32_ubyte2_e32 v154, v133
	v_cvt_f32_ubyte1_e32 v133, v134
	v_cvt_f32_ubyte0_e32 v132, v134
	v_cvt_f32_ubyte3_e32 v157, v134
	v_cvt_f32_ubyte2_e32 v156, v134
	v_cvt_f32_ubyte1_e32 v159, v135
	v_cvt_f32_ubyte0_e32 v158, v135
	v_cvt_f32_ubyte3_e32 v161, v135
	v_cvt_f32_ubyte2_e32 v160, v135
	v_cvt_f32_ubyte1_e32 v135, v136
	v_cvt_f32_ubyte0_e32 v134, v136
	v_cvt_f32_ubyte3_e32 v163, v136
	v_cvt_f32_ubyte2_e32 v162, v136
	v_cvt_f32_ubyte1_e32 v165, v137
	v_cvt_f32_ubyte0_e32 v164, v137
	v_cvt_f32_ubyte3_e32 v167, v137
	v_cvt_f32_ubyte2_e32 v166, v137
	v_pk_mul_f32 v[128:129], v[128:129], v[148:149]
	v_pk_mul_f32 v[130:131], v[130:131], v[150:151]
	v_pk_mul_f32 v[124:125], v[124:125], v[152:153]
	v_pk_mul_f32 v[126:127], v[126:127], v[154:155]
	v_pk_mul_f32 v[120:121], v[120:121], v[132:133]
	v_pk_mul_f32 v[122:123], v[122:123], v[156:157]
	v_pk_mul_f32 v[116:117], v[116:117], v[158:159]
	v_pk_mul_f32 v[118:119], v[118:119], v[160:161]
	v_pk_mul_f32 v[132:133], v[112:113], v[134:135]
	v_pk_mul_f32 v[134:135], v[114:115], v[162:163]
	v_pk_mul_f32 v[148:149], v[108:109], v[164:165]
	v_pk_mul_f32 v[150:151], v[110:111], v[166:167]
	v_cvt_pk_bf16_f32 v108, v128, v129
	v_cvt_pk_bf16_f32 v109, v130, v131
	v_cvt_pk_bf16_f32 v110, v124, v125
	v_cvt_pk_bf16_f32 v111, v126, v127
	v_cvt_pk_bf16_f32 v112, v120, v121
	v_cvt_pk_bf16_f32 v113, v122, v123
	v_cvt_pk_bf16_f32 v114, v116, v117
	v_cvt_pk_bf16_f32 v115, v118, v119
	v_cvt_pk_bf16_f32 v116, v132, v133
	v_cvt_pk_bf16_f32 v117, v134, v135
	v_cvt_pk_bf16_f32 v118, v148, v149
	v_cvt_pk_bf16_f32 v119, v150, v151
	buffer_store_dwordx4 v[108:111], v0, s[8:11], 0 offen sc1
	buffer_store_dwordx4 v[112:115], v0, s[8:11], 0 offen offset:256 sc1
	buffer_store_dwordx4 v[116:119], v170, s[8:11], 0 offen sc1
	v_cvt_f32_ubyte1_e32 v109, v139
	v_cvt_f32_ubyte0_e32 v108, v139
	v_pk_mul_f32 v[108:109], v[146:147], v[108:109]
	v_cvt_f32_ubyte1_e32 v137, v138
	v_cvt_pk_bf16_f32 v122, v108, v109
	v_cvt_f32_ubyte3_e32 v109, v139
	v_cvt_f32_ubyte2_e32 v108, v139
	v_pk_mul_f32 v[108:109], v[144:145], v[108:109]
	v_cvt_f32_ubyte0_e32 v136, v138
	v_cvt_pk_bf16_f32 v123, v108, v109
	v_pk_mul_f32 v[108:109], v[94:95], s[16:17] op_sel_hi:[1,0]
	v_pk_mul_f32 v[94:95], v[92:93], s[16:17] op_sel_hi:[1,0]
	v_cvt_f32_ubyte1_e32 v93, v104
	v_cvt_f32_ubyte0_e32 v92, v104
	v_pk_mul_f32 v[92:93], v[96:97], v[92:93]
	v_cvt_f32_ubyte3_e32 v97, v104
	v_cvt_f32_ubyte2_e32 v96, v104
	v_pk_mul_f32 v[96:97], v[98:99], v[96:97]
	v_cvt_pk_bf16_f32 v92, v92, v93
	v_cvt_pk_bf16_f32 v93, v96, v97
	v_cvt_f32_ubyte1_e32 v97, v105
	v_cvt_f32_ubyte0_e32 v96, v105
	v_cvt_f32_ubyte3_e32 v169, v138
	v_cvt_f32_ubyte2_e32 v168, v138
	v_pk_mul_f32 v[94:95], v[94:95], v[96:97]
	v_cvt_f32_ubyte3_e32 v97, v105
	v_cvt_f32_ubyte2_e32 v96, v105
	v_pk_mul_f32 v[136:137], v[142:143], v[136:137]
	v_pk_mul_f32 v[140:141], v[140:141], v[168:169]
	v_pk_mul_f32 v[96:97], v[108:109], v[96:97]
	v_cvt_pk_bf16_f32 v120, v136, v137
	v_cvt_pk_bf16_f32 v121, v140, v141
	v_add_u32_e32 v110, 0x10000, v0
	v_cvt_pk_bf16_f32 v94, v94, v95
	v_cvt_pk_bf16_f32 v95, v96, v97
	buffer_store_dwordx4 v[120:123], v170, s[8:11], 0 offen offset:256 sc1
	buffer_store_dwordx4 v[92:95], v110, s[8:11], 0 offen sc1
	s_nop 1
	v_pk_mul_f32 v[92:93], v[86:87], s[16:17] op_sel_hi:[1,0]
	v_pk_mul_f32 v[86:87], v[84:85], s[16:17] op_sel_hi:[1,0]
	v_cvt_f32_ubyte1_e32 v85, v106
	v_cvt_f32_ubyte0_e32 v84, v106
	v_pk_mul_f32 v[84:85], v[88:89], v[84:85]
	v_cvt_f32_ubyte3_e32 v89, v106
	v_cvt_f32_ubyte2_e32 v88, v106
	v_pk_mul_f32 v[88:89], v[90:91], v[88:89]
	v_cvt_pk_bf16_f32 v84, v84, v85
	v_cvt_pk_bf16_f32 v85, v88, v89
	v_cvt_f32_ubyte1_e32 v89, v107
	v_cvt_f32_ubyte0_e32 v88, v107
	v_pk_mul_f32 v[86:87], v[86:87], v[88:89]
	v_cvt_f32_ubyte3_e32 v89, v107
	v_cvt_f32_ubyte2_e32 v88, v107
	v_pk_mul_f32 v[88:89], v[92:93], v[88:89]
	v_cvt_pk_bf16_f32 v86, v86, v87
	v_cvt_pk_bf16_f32 v87, v88, v89
	buffer_store_dwordx4 v[84:87], v110, s[8:11], 0 offen offset:256 sc1
	s_nop 1
	v_pk_mul_f32 v[84:85], v[78:79], s[16:17] op_sel_hi:[1,0]
	v_pk_mul_f32 v[78:79], v[76:77], s[16:17] op_sel_hi:[1,0]
	v_cvt_f32_ubyte1_e32 v77, v100
	v_cvt_f32_ubyte0_e32 v76, v100
	v_pk_mul_f32 v[76:77], v[80:81], v[76:77]
	v_cvt_f32_ubyte3_e32 v81, v100
	v_cvt_f32_ubyte2_e32 v80, v100
	v_pk_mul_f32 v[80:81], v[82:83], v[80:81]
	v_cvt_pk_bf16_f32 v76, v76, v77
	v_cvt_pk_bf16_f32 v77, v80, v81
	v_cvt_f32_ubyte1_e32 v81, v101
	v_cvt_f32_ubyte0_e32 v80, v101
	v_pk_mul_f32 v[78:79], v[78:79], v[80:81]
	v_cvt_f32_ubyte3_e32 v81, v101
	v_cvt_f32_ubyte2_e32 v80, v101
	v_pk_mul_f32 v[80:81], v[84:85], v[80:81]
	v_add_u32_e32 v86, 0x18000, v0
	v_cvt_pk_bf16_f32 v78, v78, v79
	v_cvt_pk_bf16_f32 v79, v80, v81
	buffer_store_dwordx4 v[76:79], v86, s[8:11], 0 offen sc1
	v_add_u32_e32 v84, 0x40000, v0
	s_nop 0
	v_pk_mul_f32 v[76:77], v[70:71], s[16:17] op_sel_hi:[1,0]
	v_pk_mul_f32 v[70:71], v[68:69], s[16:17] op_sel_hi:[1,0]
	v_cvt_f32_ubyte1_e32 v69, v102
	v_cvt_f32_ubyte0_e32 v68, v102
	v_pk_mul_f32 v[68:69], v[72:73], v[68:69]
	v_cvt_f32_ubyte3_e32 v73, v102
	v_cvt_f32_ubyte2_e32 v72, v102
	v_pk_mul_f32 v[72:73], v[74:75], v[72:73]
	v_cvt_pk_bf16_f32 v68, v68, v69
	v_cvt_pk_bf16_f32 v69, v72, v73
	v_cvt_f32_ubyte1_e32 v73, v103
	v_cvt_f32_ubyte0_e32 v72, v103
	v_pk_mul_f32 v[70:71], v[70:71], v[72:73]
	v_cvt_f32_ubyte3_e32 v73, v103
	v_cvt_f32_ubyte2_e32 v72, v103
	v_pk_mul_f32 v[72:73], v[76:77], v[72:73]
	v_cvt_pk_bf16_f32 v70, v70, v71
	v_cvt_pk_bf16_f32 v71, v72, v73
	buffer_store_dwordx4 v[68:71], v86, s[8:11], 0 offen offset:256 sc1
	s_nop 0
	s_nop 0
	s_nop 0
	s_nop 0
	v_pk_mul_f32 v[2:3], v[66:67], s[16:17] op_sel_hi:[1,0]
	v_pk_mul_f32 v[66:67], v[62:63], s[16:17] op_sel_hi:[1,0]
	v_pk_mul_f32 v[62:63], v[60:61], s[16:17] op_sel_hi:[1,0]
	s_waitcnt vmcnt(8)
	v_cvt_f32_ubyte1_e32 v61, v224
	v_cvt_f32_ubyte0_e32 v60, v224
	v_pk_mul_f32 v[60:61], v[64:65], v[60:61]
	v_cvt_f32_ubyte3_e32 v65, v224
	v_cvt_f32_ubyte2_e32 v64, v224
	v_pk_mul_f32 v[2:3], v[2:3], v[64:65]
	v_cvt_pk_bf16_f32 v60, v60, v61
	v_cvt_pk_bf16_f32 v61, v2, v3
	v_cvt_f32_ubyte1_e32 v3, v225
	v_cvt_f32_ubyte0_e32 v2, v225
	v_pk_mul_f32 v[2:3], v[62:63], v[2:3]
	s_nop 0
	v_cvt_pk_bf16_f32 v62, v2, v3
	v_cvt_f32_ubyte3_e32 v3, v225
	v_cvt_f32_ubyte2_e32 v2, v225
	v_pk_mul_f32 v[2:3], v[66:67], v[2:3]
	s_nop 0
	v_cvt_pk_bf16_f32 v63, v2, v3
	v_pk_mul_f32 v[2:3], v[58:59], s[16:17] op_sel_hi:[1,0]
	v_pk_mul_f32 v[58:59], v[54:55], s[16:17] op_sel_hi:[1,0]
	v_pk_mul_f32 v[54:55], v[52:53], s[16:17] op_sel_hi:[1,0]
	v_cvt_f32_ubyte1_e32 v53, v226
	v_cvt_f32_ubyte0_e32 v52, v226
	v_pk_mul_f32 v[52:53], v[56:57], v[52:53]
	v_cvt_f32_ubyte3_e32 v57, v226
	v_cvt_f32_ubyte2_e32 v56, v226
	v_pk_mul_f32 v[2:3], v[2:3], v[56:57]
	v_cvt_pk_bf16_f32 v52, v52, v53
	v_cvt_pk_bf16_f32 v53, v2, v3
	v_cvt_f32_ubyte1_e32 v3, v227
	v_cvt_f32_ubyte0_e32 v2, v227
	v_pk_mul_f32 v[2:3], v[54:55], v[2:3]
	buffer_store_dwordx4 v[60:63], v84, s[8:11], 0 offen sc1
	v_cvt_pk_bf16_f32 v54, v2, v3
	v_cvt_f32_ubyte3_e32 v3, v227
	v_cvt_f32_ubyte2_e32 v2, v227
	v_pk_mul_f32 v[2:3], v[58:59], v[2:3]
	s_nop 0
	v_cvt_pk_bf16_f32 v55, v2, v3
	v_pk_mul_f32 v[2:3], v[50:51], s[16:17] op_sel_hi:[1,0]
	v_pk_mul_f32 v[50:51], v[46:47], s[16:17] op_sel_hi:[1,0]
	v_pk_mul_f32 v[46:47], v[44:45], s[16:17] op_sel_hi:[1,0]
	s_nop 0
	v_cvt_f32_ubyte1_e32 v45, v228
	v_cvt_f32_ubyte0_e32 v44, v228
	v_pk_mul_f32 v[44:45], v[48:49], v[44:45]
	v_cvt_f32_ubyte3_e32 v49, v228
	v_cvt_f32_ubyte2_e32 v48, v228
	v_pk_mul_f32 v[2:3], v[2:3], v[48:49]
	v_cvt_pk_bf16_f32 v44, v44, v45
	v_cvt_pk_bf16_f32 v45, v2, v3
	v_cvt_f32_ubyte1_e32 v3, v229
	v_cvt_f32_ubyte0_e32 v2, v229
	v_pk_mul_f32 v[2:3], v[46:47], v[2:3]
	buffer_store_dwordx4 v[52:55], v84, s[8:11], 0 offen offset:256 sc1
	v_cvt_pk_bf16_f32 v46, v2, v3
	v_cvt_f32_ubyte3_e32 v3, v229
	v_cvt_f32_ubyte2_e32 v2, v229
	v_pk_mul_f32 v[2:3], v[50:51], v[2:3]
	v_add_u32_e32 v52, 0x48000, v0
	v_cvt_pk_bf16_f32 v47, v2, v3
	v_pk_mul_f32 v[2:3], v[42:43], s[16:17] op_sel_hi:[1,0]
	v_pk_mul_f32 v[42:43], v[38:39], s[16:17] op_sel_hi:[1,0]
	v_pk_mul_f32 v[38:39], v[36:37], s[16:17] op_sel_hi:[1,0]
	v_cvt_f32_ubyte1_e32 v37, v230
	v_cvt_f32_ubyte0_e32 v36, v230
	v_pk_mul_f32 v[36:37], v[40:41], v[36:37]
	v_cvt_f32_ubyte3_e32 v41, v230
	v_cvt_f32_ubyte2_e32 v40, v230
	v_pk_mul_f32 v[2:3], v[2:3], v[40:41]
	v_cvt_pk_bf16_f32 v36, v36, v37
	v_cvt_pk_bf16_f32 v37, v2, v3
	v_cvt_f32_ubyte1_e32 v3, v231
	v_cvt_f32_ubyte0_e32 v2, v231
	v_pk_mul_f32 v[2:3], v[38:39], v[2:3]
	buffer_store_dwordx4 v[44:47], v52, s[8:11], 0 offen sc1
	v_cvt_pk_bf16_f32 v38, v2, v3
	v_cvt_f32_ubyte3_e32 v3, v231
	v_cvt_f32_ubyte2_e32 v2, v231
	v_pk_mul_f32 v[2:3], v[42:43], v[2:3]
	s_nop 0
	v_cvt_pk_bf16_f32 v39, v2, v3
	v_pk_mul_f32 v[2:3], v[34:35], s[16:17] op_sel_hi:[1,0]
	v_pk_mul_f32 v[34:35], v[30:31], s[16:17] op_sel_hi:[1,0]
	v_pk_mul_f32 v[30:31], v[28:29], s[16:17] op_sel_hi:[1,0]
	s_nop 0
	v_cvt_f32_ubyte1_e32 v29, v232
	v_cvt_f32_ubyte0_e32 v28, v232
	v_pk_mul_f32 v[28:29], v[32:33], v[28:29]
	v_cvt_f32_ubyte3_e32 v33, v232
	v_cvt_f32_ubyte2_e32 v32, v232
	v_pk_mul_f32 v[2:3], v[2:3], v[32:33]
	v_cvt_pk_bf16_f32 v28, v28, v29
	v_cvt_pk_bf16_f32 v29, v2, v3
	v_cvt_f32_ubyte1_e32 v3, v233
	v_cvt_f32_ubyte0_e32 v2, v233
	v_pk_mul_f32 v[2:3], v[30:31], v[2:3]
	buffer_store_dwordx4 v[36:39], v52, s[8:11], 0 offen offset:256 sc1
	v_cvt_pk_bf16_f32 v30, v2, v3
	v_cvt_f32_ubyte3_e32 v3, v233
	v_cvt_f32_ubyte2_e32 v2, v233
	v_pk_mul_f32 v[2:3], v[34:35], v[2:3]
	v_add_u32_e32 v36, 0x50000, v0
	v_cvt_pk_bf16_f32 v31, v2, v3
	v_pk_mul_f32 v[2:3], v[26:27], s[16:17] op_sel_hi:[1,0]
	v_pk_mul_f32 v[26:27], v[22:23], s[16:17] op_sel_hi:[1,0]
	v_pk_mul_f32 v[22:23], v[20:21], s[16:17] op_sel_hi:[1,0]
	v_cvt_f32_ubyte1_e32 v21, v234
	v_cvt_f32_ubyte0_e32 v20, v234
	v_pk_mul_f32 v[20:21], v[24:25], v[20:21]
	v_cvt_f32_ubyte3_e32 v25, v234
	v_cvt_f32_ubyte2_e32 v24, v234
	v_pk_mul_f32 v[2:3], v[2:3], v[24:25]
	v_cvt_pk_bf16_f32 v20, v20, v21
	v_cvt_pk_bf16_f32 v21, v2, v3
	v_cvt_f32_ubyte1_e32 v3, v235
	v_cvt_f32_ubyte0_e32 v2, v235
	v_pk_mul_f32 v[2:3], v[22:23], v[2:3]
	v_add_u32_e32 v0, 0x58000, v0
	v_cvt_pk_bf16_f32 v22, v2, v3
	v_cvt_f32_ubyte3_e32 v3, v235
	v_cvt_f32_ubyte2_e32 v2, v235
	v_pk_mul_f32 v[2:3], v[26:27], v[2:3]
	buffer_store_dwordx4 v[28:31], v36, s[8:11], 0 offen sc1
	v_cvt_pk_bf16_f32 v23, v2, v3
	v_pk_mul_f32 v[2:3], v[18:19], s[16:17] op_sel_hi:[1,0]
	v_pk_mul_f32 v[18:19], v[14:15], s[16:17] op_sel_hi:[1,0]
	v_pk_mul_f32 v[14:15], v[12:13], s[16:17] op_sel_hi:[1,0]
	s_nop 0
	v_cvt_f32_ubyte1_e32 v13, v236
	v_cvt_f32_ubyte0_e32 v12, v236
	v_pk_mul_f32 v[12:13], v[16:17], v[12:13]
	v_cvt_f32_ubyte3_e32 v17, v236
	v_cvt_f32_ubyte2_e32 v16, v236
	v_pk_mul_f32 v[2:3], v[2:3], v[16:17]
	v_cvt_pk_bf16_f32 v12, v12, v13
	v_cvt_pk_bf16_f32 v13, v2, v3
	v_cvt_f32_ubyte1_e32 v3, v237
	v_cvt_f32_ubyte0_e32 v2, v237
	v_pk_mul_f32 v[2:3], v[14:15], v[2:3]
	buffer_store_dwordx4 v[20:23], v36, s[8:11], 0 offen offset:256 sc1
	v_cvt_pk_bf16_f32 v14, v2, v3
	v_cvt_f32_ubyte3_e32 v3, v237
	v_cvt_f32_ubyte2_e32 v2, v237
	v_pk_mul_f32 v[2:3], v[18:19], v[2:3]
	s_nop 0
	v_cvt_pk_bf16_f32 v15, v2, v3
	v_pk_mul_f32 v[2:3], v[8:9], s[16:17] op_sel_hi:[1,0]
	v_cvt_f32_ubyte1_e32 v9, v238
	v_cvt_f32_ubyte0_e32 v8, v238
	v_pk_mul_f32 v[2:3], v[2:3], v[8:9]
	v_cvt_f32_ubyte3_e32 v9, v238
	v_cvt_f32_ubyte2_e32 v8, v238
	v_pk_mul_f32 v[8:9], v[10:11], v[8:9]
	v_cvt_pk_bf16_f32 v2, v2, v3
	v_cvt_pk_bf16_f32 v3, v8, v9
	v_cvt_f32_ubyte1_e32 v9, v239
	v_cvt_f32_ubyte0_e32 v8, v239
	v_pk_mul_f32 v[4:5], v[4:5], v[8:9]
	v_cvt_f32_ubyte3_e32 v9, v239
	v_cvt_f32_ubyte2_e32 v8, v239
	v_pk_mul_f32 v[6:7], v[6:7], v[8:9]
	v_cvt_pk_bf16_f32 v4, v4, v5
	v_cvt_pk_bf16_f32 v5, v6, v7
	buffer_store_dwordx4 v[12:15], v0, s[8:11], 0 offen sc1
	buffer_store_dwordx4 v[2:5], v0, s[8:11], 0 offen offset:256 sc1
	s_cbranch_vccnz .LBB0_431
